# P12 final rows: lane-to-column remap so every f32 output store instruction writes a contiguous 1 KiB (inputs read as 8-byte pieces, gains re-offset)
# speedup vs baseline: 1.0078x; 1.0022x over previous
.LBB0_1549:
	s_cmp_lt_i32 s86, 13
	s_cselect_b64 s[2:3], -1, 0
	s_and_b64 s[0:1], s[2:3], s[0:1]
	s_andn2_b64 vcc, exec, s[0:1]
	s_cbranch_vccnz .LBB0_1555
	s_add_i32 s0, 0, 0x27ed8
	v_mov_b32_e32 v0, s0
	ds_read2_b64 v[0:3], v0 offset1:1
	v_readfirstlane_b32 s4, v182
	s_lshl_b32 s1, s81, 3
	s_ashr_i32 s4, s4, 6
	s_add_i32 s4, s4, s1
	s_waitcnt lgkmcnt(0)
	v_readfirstlane_b32 s2, v0
	v_readfirstlane_b32 s3, v1
	v_readfirstlane_b32 s0, v2
	s_cmp_gt_i32 s4, 0xffff
	v_readfirstlane_b32 s1, v3
	s_cbranch_scc1 .LBB0_1555
	s_waitcnt vmcnt(0)
	v_and_b32_e32 v36, 63, v182
	v_lshlrev_b32_e32 v32, 4, v36
	v_mov_b32_e32 v33, 0
	v_lshl_add_u64 v[16:17], s[2:3], 0, v[32:33]
	v_lshl_add_u64 v[34:35], s[0:1], 0, v[32:33]
	flat_load_dwordx4 v[0:3], v[16:17]
	flat_load_dwordx4 v[4:7], v[16:17] offset:1024
	flat_load_dwordx4 v[8:11], v[16:17] offset:2048
	flat_load_dwordx4 v[12:15], v[16:17] offset:3072
	s_nop 0
	flat_load_dwordx4 v[16:19], v[34:35]
	flat_load_dwordx4 v[20:23], v[34:35] offset:1024
	flat_load_dwordx4 v[24:27], v[34:35] offset:2048
	flat_load_dwordx4 v[28:31], v[34:35] offset:3072
	v_lshlrev_b32_e32 v34, 3, v36
	v_mbcnt_lo_u32_b32 v36, -1, 0
	v_mbcnt_hi_u32_b32 v36, -1, v36
	v_and_b32_e32 v37, 64, v36
	v_add_u32_e32 v37, 64, v37
	v_xor_b32_e32 v38, 1, v36
	v_cmp_lt_i32_e32 vcc, v38, v37
	v_readlane_b32 s0, v254, 0
	v_readlane_b32 s1, v254, 1
	v_cndmask_b32_e32 v38, v36, v38, vcc
	v_lshlrev_b32_e32 v70, 2, v38
	v_xor_b32_e32 v38, 2, v36
	v_cmp_lt_i32_e32 vcc, v38, v37
	s_load_dwordx2 s[0:1], s[0:1], 0xe8
	v_mov_b32_e32 v35, v33
	v_cndmask_b32_e32 v38, v36, v38, vcc
	v_lshlrev_b32_e32 v71, 2, v38
	v_xor_b32_e32 v38, 4, v36
	v_cmp_lt_i32_e32 vcc, v38, v37
	v_lshl_add_u64 v[34:35], s[84:85], 0, v[34:35]
	s_mov_b64 s[2:3], 0xc000000
	v_cndmask_b32_e32 v38, v36, v38, vcc
	v_lshlrev_b32_e32 v72, 2, v38
	v_xor_b32_e32 v38, 8, v36
	v_cmp_lt_i32_e32 vcc, v38, v37
	v_lshl_add_u64 v[40:41], v[34:35], 0, s[2:3]
	s_mov_b64 s[2:3], 0x32000000
	v_cndmask_b32_e32 v38, v36, v38, vcc
	v_lshlrev_b32_e32 v73, 2, v38
	v_xor_b32_e32 v38, 16, v36
	v_cmp_lt_i32_e32 vcc, v38, v37
	v_lshl_add_u64 v[42:43], v[34:35], 0, s[2:3]
	s_waitcnt lgkmcnt(0)
	v_lshl_add_u64 v[44:45], s[0:1], 0, v[32:33]
	v_cndmask_b32_e32 v38, v36, v38, vcc
	v_lshlrev_b32_e32 v74, 2, v38
	v_xor_b32_e32 v38, 32, v36
	v_cmp_lt_i32_e32 vcc, v38, v37
	v_mov_b32_e32 v76, 0x358637bd
	s_mov_b32 s8, 0xf800000
	v_cndmask_b32_e32 v36, v36, v38, vcc
	v_lshlrev_b32_e32 v75, 2, v36
	v_mov_b32_e32 v77, 0x260
	s_branch .LBB0_1553

.LBB0_1553:
	s_ashr_i32 s5, s4, 31
	s_lshl_b64 s[0:1], s[4:5], 11
	v_lshl_add_u64 v[36:37], v[40:41], 0, s[0:1]
	global_load_dwordx2 v[32:33], v[36:37], off
	global_load_dwordx2 v[34:35], v[36:37], off offset:512
	global_load_dwordx2 v[46:47], v[36:37], off offset:1024
	global_load_dwordx2 v[48:49], v[36:37], off offset:1536
	v_lshl_add_u64 v[36:37], v[42:43], 0, s[0:1]
	s_add_i32 s6, s4, s83
	s_waitcnt lgkmcnt(0)
	global_load_dwordx2 v[50:51], v[36:37], off
	global_load_dwordx2 v[52:53], v[36:37], off offset:512
	global_load_dwordx2 v[54:55], v[36:37], off offset:1024
	global_load_dwordx2 v[56:57], v[36:37], off offset:1536
	s_min_i32 s0, s6, 0xffff
	s_ashr_i32 s1, s0, 31
	s_lshl_b64 s[0:1], s[0:1], 11
	v_lshl_add_u64 v[58:59], v[42:43], 0, s[0:1]
	global_load_dwordx2 v[36:37], v[58:59], off
	global_load_dwordx2 v[38:39], v[58:59], off offset:512
	s_waitcnt vmcnt(0)
	v_and_b32_e32 v61, 0xffff0000, v32
	v_and_b32_e32 v63, 0xffff0000, v33
	v_and_b32_e32 v65, 0xffff0000, v34
	v_and_b32_e32 v83, 0xffff0000, v35
	v_lshlrev_b32_e32 v60, 16, v32
	v_lshlrev_b32_e32 v62, 16, v33
	v_lshlrev_b32_e32 v64, 16, v34
	v_lshlrev_b32_e32 v82, 16, v35
	v_and_b32_e32 v85, 0xffff0000, v46
	v_and_b32_e32 v87, 0xffff0000, v47
	v_mul_f32_e32 v32, v61, v61
	v_mul_f32_e32 v33, v63, v63
	v_mul_f32_e32 v34, v65, v65
	v_mul_f32_e32 v35, v83, v83
	v_lshlrev_b32_e32 v84, 16, v46
	v_lshlrev_b32_e32 v86, 16, v47
	v_and_b32_e32 v89, 0xffff0000, v48
	v_and_b32_e32 v91, 0xffff0000, v49
	v_mul_f32_e32 v46, v85, v85
	v_mul_f32_e32 v47, v87, v87
	v_fmac_f32_e32 v32, v60, v60
	v_fmac_f32_e32 v33, v62, v62
	v_fmac_f32_e32 v34, v64, v64
	v_fmac_f32_e32 v35, v82, v82
	v_lshlrev_b32_e32 v88, 16, v48
	v_lshlrev_b32_e32 v90, 16, v49
	v_mul_f32_e32 v48, v89, v89
	v_mul_f32_e32 v49, v91, v91
	v_fmac_f32_e32 v46, v84, v84
	v_fmac_f32_e32 v47, v86, v86
	v_add_f32_e32 v32, v32, v33
	v_add_f32_e32 v33, v34, v35
	v_fmac_f32_e32 v48, v88, v88
	v_fmac_f32_e32 v49, v90, v90
	v_add_f32_e32 v34, v46, v47
	v_add_f32_e32 v32, v32, v33
	v_add_f32_e32 v35, v48, v49
	v_add_f32_e32 v32, v32, v34
	v_add_f32_e32 v48, v35, v32
	s_nop 1
	global_load_dwordx2 v[32:33], v[58:59], off offset:1024
	global_load_dwordx2 v[34:35], v[58:59], off offset:1536
	v_lshl_add_u64 v[46:47], v[40:41], 0, s[0:1]
	global_load_dwordx2 v[66:67], v[46:47], off
	global_load_dwordx2 v[68:69], v[46:47], off offset:512
	global_load_dwordx2 v[78:79], v[46:47], off offset:1024
	global_load_dwordx2 v[80:81], v[46:47], off offset:1536
	v_lshlrev_b32_e32 v58, 16, v50
	s_waitcnt lgkmcnt(0)
	v_add_f32_dpp v48, v48, v48 quad_perm:[1,0,3,2] row_mask:0xf bank_mask:0xf
	s_nop 1
	v_and_b32_e32 v59, 0xffff0000, v50
	v_lshlrev_b32_e32 v92, 16, v51
	v_and_b32_e32 v93, 0xffff0000, v51
	v_lshlrev_b32_e32 v94, 16, v52
	s_waitcnt lgkmcnt(0)
	v_add_f32_dpp v46, v48, v48 quad_perm:[2,3,0,1] row_mask:0xf bank_mask:0xf
	s_nop 1
	v_lshlrev_b32_e32 v48, 16, v37
	v_and_b32_e32 v95, 0xffff0000, v52
	v_lshlrev_b32_e32 v96, 16, v53
	v_and_b32_e32 v97, 0xffff0000, v53
	s_waitcnt lgkmcnt(0)
	v_add_f32_dpp v46, v46, v46 row_half_mirror row_mask:0xf bank_mask:0xf
	s_nop 1
	v_lshlrev_b32_e32 v98, 16, v54
	v_and_b32_e32 v99, 0xffff0000, v54
	v_lshlrev_b32_e32 v100, 16, v55
	v_and_b32_e32 v101, 0xffff0000, v55
	s_waitcnt lgkmcnt(0)
	v_add_f32_dpp v46, v46, v46 row_mirror row_mask:0xf bank_mask:0xf
	v_mov_b32_e32 v47, v46
	v_lshlrev_b32_e32 v102, 16, v56
	v_and_b32_e32 v103, 0xffff0000, v56
	v_lshlrev_b32_e32 v104, 16, v57
	v_and_b32_e32 v105, 0xffff0000, v57
	s_waitcnt lgkmcnt(0)
	v_permlane16_swap_b32_e32 v46, v47
	v_add_f32_e32 v49, v46, v47
	v_mov_b32_e32 v50, v49
	v_lshlrev_b32_e32 v46, 16, v36
	v_and_b32_e32 v47, 0xffff0000, v36
	s_waitcnt lgkmcnt(0)
	v_permlane32_swap_b32_e32 v49, v50
	v_add_f32_e32 v36, v49, v50
	v_fmamk_f32 v36, v36, 0x3a800000, v76
	v_mul_f32_e32 v49, 0x4f800000, v36
	v_cmp_gt_f32_e32 vcc, s8, v36
	s_nop 1
	v_cndmask_b32_e32 v50, v36, v49, vcc
	v_sqrt_f32_e32 v51, v50
	v_and_b32_e32 v49, 0xffff0000, v37
	v_lshlrev_b32_e32 v36, 16, v38
	v_and_b32_e32 v37, 0xffff0000, v38
	v_add_u32_e32 v38, -1, v51
	v_add_u32_e32 v52, 1, v51
	v_fma_f32 v53, -v38, v51, v50
	v_fma_f32 v54, -v52, v51, v50
	v_cmp_ge_f32_e64 s[0:1], 0, v53
	s_nop 1
	v_cndmask_b32_e64 v38, v51, v38, s[0:1]
	v_cmp_lt_f32_e64 s[0:1], 0, v54
	s_nop 1
	v_cndmask_b32_e64 v38, v38, v52, s[0:1]
	v_mul_f32_e32 v51, 0x37800000, v38
	v_cndmask_b32_e32 v38, v38, v51, vcc
	v_cmp_class_f32_e32 vcc, v50, v77
	s_nop 1
	v_cndmask_b32_e32 v50, v38, v50, vcc
	v_div_scale_f32 v51, s[0:1], v50, v50, 1.0
	v_rcp_f32_e32 v52, v51
	v_div_scale_f32 v53, vcc, 1.0, v50, 1.0
	v_lshlrev_b32_e32 v38, 16, v39
	v_fma_f32 v54, -v51, v52, 1.0
	v_fmac_f32_e32 v52, v54, v52
	v_mul_f32_e32 v54, v53, v52
	v_fma_f32 v55, -v51, v54, v53
	v_fmac_f32_e32 v54, v55, v52
	v_fma_f32 v51, -v51, v54, v53
	v_div_fmas_f32 v51, v51, v52, v54
	v_div_fixup_f32 v50, v51, v50, 1.0
	v_mul_f32_e32 v50, 0.5, v50
	v_pk_mul_f32 v[52:53], v[50:51], v[62:63] op_sel_hi:[0,1]
	v_pk_mul_f32 v[54:55], v[50:51], v[60:61] op_sel_hi:[0,1]
	v_pk_mul_f32 v[56:57], v[50:51], v[82:83] op_sel_hi:[0,1]
	v_pk_mul_f32 v[60:61], v[50:51], v[64:65] op_sel_hi:[0,1]
	v_pk_mul_f32 v[62:63], v[50:51], v[84:85] op_sel_hi:[0,1]
	v_pk_mul_f32 v[64:65], v[50:51], v[86:87] op_sel_hi:[0,1]
	v_pk_mul_f32 v[82:83], v[50:51], v[88:89] op_sel_hi:[0,1]
	v_pk_mul_f32 v[84:85], v[50:51], v[90:91] op_sel_hi:[0,1]
	v_pk_fma_f32 v[50:51], v[0:1], v[54:55], v[58:59]
	v_pk_fma_f32 v[52:53], v[2:3], v[52:53], v[92:93]
	v_pk_fma_f32 v[54:55], v[4:5], v[60:61], v[94:95]
	v_pk_fma_f32 v[56:57], v[6:7], v[56:57], v[96:97]
	v_pk_fma_f32 v[58:59], v[10:11], v[64:65], v[100:101]
	v_pk_fma_f32 v[60:61], v[8:9], v[62:63], v[98:99]
	v_pk_fma_f32 v[62:63], v[14:15], v[84:85], v[104:105]
	v_pk_fma_f32 v[64:65], v[12:13], v[82:83], v[102:103]
	v_pk_mul_f32 v[82:83], v[52:53], v[52:53]
	v_pk_mul_f32 v[84:85], v[50:51], v[50:51]
	v_pk_mul_f32 v[86:87], v[56:57], v[56:57]
	v_pk_mul_f32 v[88:89], v[54:55], v[54:55]
	v_pk_mov_b32 v[94:95], v[84:85], v[82:83] op_sel:[1,0]
	v_mov_b32_e32 v85, v83
	v_pk_mov_b32 v[82:83], v[88:89], v[86:87] op_sel:[1,0]
	v_mov_b32_e32 v89, v87
	v_mul_f32_e32 v90, v60, v60
	v_mul_f32_e32 v92, v58, v58
	v_pk_add_f32 v[84:85], v[94:95], v[84:85]
	v_pk_add_f32 v[82:83], v[82:83], v[88:89]
	v_pk_fma_f32 v[86:87], v[60:61], v[60:61], v[90:91] op_sel_hi:[1,1,0]
	v_pk_fma_f32 v[90:91], v[58:59], v[58:59], v[92:93] op_sel_hi:[1,1,0]
	v_pk_add_f32 v[84:85], v[84:85], v[84:85] op_sel_hi:[0,1]
	v_pk_add_f32 v[82:83], v[82:83], v[82:83] op_sel_hi:[0,1]
	v_mul_f32_e32 v86, v64, v64
	v_mul_f32_e32 v90, v65, v65
	v_mul_f32_e32 v84, v62, v62
	v_mul_f32_e32 v82, v63, v63
	v_pk_add_f32 v[86:87], v[86:87], v[90:91]
	v_pk_add_f32 v[82:83], v[84:85], v[82:83]
	s_waitcnt vmcnt(4)
	v_lshlrev_b32_e32 v84, 16, v33
	v_pk_add_f32 v[82:83], v[86:87], v[82:83]
	s_waitcnt vmcnt(0)
	v_lshlrev_b32_e32 v90, 16, v78
	v_add_f32_e32 v85, v82, v83
	s_nop 1
	v_lshlrev_b32_e32 v82, 16, v32
	v_and_b32_e32 v83, 0xffff0000, v32
	v_lshlrev_b32_e32 v32, 16, v34
	v_lshlrev_b32_e32 v92, 16, v80
	s_waitcnt lgkmcnt(0)
	v_add_f32_dpp v87, v85, v85 quad_perm:[1,0,3,2] row_mask:0xf bank_mask:0xf
	s_nop 1
	v_and_b32_e32 v85, 0xffff0000, v33
	v_and_b32_e32 v33, 0xffff0000, v34
	v_lshlrev_b32_e32 v86, 16, v66
	v_and_b32_e32 v39, 0xffff0000, v39
	s_waitcnt lgkmcnt(0)
	v_add_f32_dpp v34, v87, v87 quad_perm:[2,3,0,1] row_mask:0xf bank_mask:0xf
	s_nop 1
	v_and_b32_e32 v87, 0xffff0000, v66
	v_lshlrev_b32_e32 v66, 16, v67
	v_and_b32_e32 v67, 0xffff0000, v67
	v_mul_f32_e32 v95, v87, v87
	s_waitcnt lgkmcnt(0)
	v_add_f32_dpp v34, v34, v34 row_half_mirror row_mask:0xf bank_mask:0xf
	s_nop 1
	v_mul_f32_e32 v96, v67, v67
	v_lshlrev_b32_e32 v88, 16, v68
	v_and_b32_e32 v89, 0xffff0000, v68
	v_lshlrev_b32_e32 v68, 16, v69
	v_and_b32_e32 v69, 0xffff0000, v69
	s_waitcnt lgkmcnt(0)
	v_add_f32_dpp v34, v34, v34 row_mirror row_mask:0xf bank_mask:0xf
	v_fmac_f32_e32 v95, v86, v86
	v_fmac_f32_e32 v96, v66, v66
	v_mov_b32_e32 v93, v34
	v_add_f32_e32 v95, v95, v96
	v_mul_f32_e32 v96, v89, v89
	v_mul_f32_e32 v97, v69, v69
	v_fmac_f32_e32 v96, v88, v88
	v_fmac_f32_e32 v97, v68, v68
	v_and_b32_e32 v91, 0xffff0000, v78
	v_lshlrev_b32_e32 v78, 16, v79
	v_and_b32_e32 v79, 0xffff0000, v79
	v_add_f32_e32 v96, v96, v97
	v_add_f32_e32 v95, v95, v96
	v_mul_f32_e32 v96, v91, v91
	v_mul_f32_e32 v97, v79, v79
	v_fmac_f32_e32 v96, v90, v90
	v_fmac_f32_e32 v97, v78, v78
	s_waitcnt lgkmcnt(0)
	v_permlane16_swap_b32_e32 v34, v93
	v_add_f32_e32 v34, v34, v93
	v_and_b32_e32 v93, 0xffff0000, v80
	v_lshlrev_b32_e32 v80, 16, v81
	v_and_b32_e32 v81, 0xffff0000, v81
	v_add_f32_e32 v96, v96, v97
	v_add_f32_e32 v95, v95, v96
	v_mul_f32_e32 v96, v93, v93
	v_mul_f32_e32 v97, v81, v81
	v_fmac_f32_e32 v96, v92, v92
	v_fmac_f32_e32 v97, v80, v80
	v_add_f32_e32 v96, v96, v97
	v_add_f32_e32 v95, v96, v95
	s_nop 1
	v_mov_b32_e32 v94, v34
	s_waitcnt lgkmcnt(0)
	v_add_f32_dpp v95, v95, v95 quad_perm:[1,0,3,2] row_mask:0xf bank_mask:0xf
	s_nop 1
	s_waitcnt lgkmcnt(0)
	v_permlane32_swap_b32_e32 v34, v94
	v_add_f32_e32 v34, v34, v94
	v_fmamk_f32 v34, v34, 0x3a800000, v76
	v_mul_f32_e32 v94, 0x4f800000, v34
	v_cmp_gt_f32_e32 vcc, s8, v34
	s_waitcnt lgkmcnt(0)
	v_add_f32_dpp v95, v95, v95 quad_perm:[2,3,0,1] row_mask:0xf bank_mask:0xf
	s_nop 1
	v_cndmask_b32_e32 v34, v34, v94, vcc
	v_sqrt_f32_e32 v97, v34
	v_lshlrev_b32_e32 v94, 16, v35
	s_waitcnt lgkmcnt(0)
	v_add_f32_dpp v95, v95, v95 row_half_mirror row_mask:0xf bank_mask:0xf
	v_add_u32_e32 v98, -1, v97
	v_fma_f32 v99, -v98, v97, v34
	v_cmp_ge_f32_e64 s[0:1], 0, v99
	v_add_u32_e32 v99, 1, v97
	s_nop 1
	v_cndmask_b32_e64 v98, v97, v98, s[0:1]
	v_fma_f32 v97, -v99, v97, v34
	v_cmp_lt_f32_e64 s[0:1], 0, v97
	s_nop 1
	v_cndmask_b32_e64 v97, v98, v99, s[0:1]
	v_mul_f32_e32 v98, 0x37800000, v97
	v_cndmask_b32_e32 v97, v97, v98, vcc
	v_cmp_class_f32_e32 vcc, v34, v77
	s_nop 1
	v_cndmask_b32_e32 v97, v97, v34, vcc
	s_waitcnt lgkmcnt(0)
	v_add_f32_dpp v34, v95, v95 row_mirror row_mask:0xf bank_mask:0xf
	v_mov_b32_e32 v96, v34
	v_and_b32_e32 v95, 0xffff0000, v35
	v_div_scale_f32 v98, s[0:1], v97, v97, 1.0
	v_rcp_f32_e32 v99, v98
	s_waitcnt lgkmcnt(0)
	v_permlane16_swap_b32_e32 v34, v96
	v_add_f32_e32 v34, v34, v96
	v_mov_b32_e32 v35, v34
	v_fma_f32 v96, -v98, v99, 1.0
	v_fmac_f32_e32 v99, v96, v99
	v_div_scale_f32 v96, vcc, 1.0, v97, 1.0
	s_waitcnt lgkmcnt(0)
	v_permlane32_swap_b32_e32 v34, v35
	v_add_f32_e32 v34, v34, v35
	v_fmamk_f32 v34, v34, 0x3a800000, v76
	v_mul_f32_e32 v35, 0x4f800000, v34
	v_cmp_gt_f32_e64 s[0:1], s8, v34
	v_mul_f32_e32 v100, v96, v99
	v_fma_f32 v101, -v98, v100, v96
	v_cndmask_b32_e64 v34, v34, v35, s[0:1]
	v_sqrt_f32_e32 v35, v34
	v_fmac_f32_e32 v100, v101, v99
	v_fma_f32 v96, -v98, v100, v96
	v_div_fmas_f32 v98, v96, v99, v100
	v_add_u32_e32 v101, -1, v35
	v_fma_f32 v102, -v101, v35, v34
	v_cmp_ge_f32_e64 s[2:3], 0, v102
	v_add_u32_e32 v102, 1, v35
	s_nop 0
	v_cndmask_b32_e64 v101, v35, v101, s[2:3]
	v_fma_f32 v35, -v102, v35, v34
	v_cmp_lt_f32_e64 s[2:3], 0, v35
	s_nop 1
	v_cndmask_b32_e64 v35, v101, v102, s[2:3]
	v_mul_f32_e32 v101, 0x37800000, v35
	v_cndmask_b32_e64 v35, v35, v101, s[0:1]
	v_cmp_class_f32_e64 s[0:1], v34, v77
	s_nop 1
	v_cndmask_b32_e64 v34, v35, v34, s[0:1]
	v_div_scale_f32 v35, s[0:1], v34, v34, 1.0
	v_rcp_f32_e32 v101, v35
	s_lshl_b64 s[0:1], s[4:5], 12
	s_cmp_gt_i32 s6, 0xffff
	v_fma_f32 v96, -v35, v101, 1.0
	v_fmac_f32_e32 v101, v96, v101
	v_div_scale_f32 v96, vcc, 1.0, v34, 1.0
	v_mul_f32_e32 v99, v96, v101
	v_fma_f32 v100, -v35, v99, v96
	v_fmac_f32_e32 v99, v100, v101
	v_fma_f32 v35, -v35, v99, v96
	v_div_fmas_f32 v35, v35, v101, v99
	v_div_fixup_f32 v34, v35, v34, 1.0
	v_mul_f32_e32 v96, 0.5, v34
	v_pk_mul_f32 v[34:35], v[96:97], v[66:67] op_sel_hi:[0,1]
	v_pk_mul_f32 v[86:87], v[96:97], v[86:87] op_sel_hi:[0,1]
	v_pk_fma_f32 v[34:35], v[2:3], v[34:35], v[48:49]
	v_pk_mul_f32 v[48:49], v[96:97], v[88:89] op_sel_hi:[0,1]
	v_pk_fma_f32 v[46:47], v[0:1], v[86:87], v[46:47]
	v_pk_fma_f32 v[36:37], v[4:5], v[48:49], v[36:37]
	v_pk_mul_f32 v[48:49], v[96:97], v[78:79] op_sel_hi:[0,1]
	v_pk_mul_f32 v[78:79], v[96:97], v[92:93] op_sel_hi:[0,1]
	v_pk_mul_f32 v[66:67], v[96:97], v[68:69] op_sel_hi:[0,1]
	v_pk_fma_f32 v[32:33], v[12:13], v[78:79], v[32:33]
	v_mul_f32_e32 v78, v47, v47
	v_mul_f32_e32 v79, v35, v35
	v_pk_fma_f32 v[38:39], v[6:7], v[66:67], v[38:39]
	v_fmac_f32_e32 v78, v46, v46
	v_fmac_f32_e32 v79, v34, v34
	v_pk_mul_f32 v[68:69], v[96:97], v[80:81] op_sel_hi:[0,1]
	v_add_f32_e32 v78, v78, v79
	v_mul_f32_e32 v79, v37, v37
	v_mul_f32_e32 v80, v39, v39
	v_pk_mul_f32 v[66:67], v[96:97], v[90:91] op_sel_hi:[0,1]
	v_fmac_f32_e32 v79, v36, v36
	v_fmac_f32_e32 v80, v38, v38
	v_pk_fma_f32 v[48:49], v[10:11], v[48:49], v[84:85]
	v_pk_fma_f32 v[66:67], v[8:9], v[66:67], v[82:83]
	v_add_f32_e32 v79, v79, v80
	v_add_f32_e32 v78, v78, v79
	v_mul_f32_e32 v79, v67, v67
	v_mul_f32_e32 v80, v49, v49
	v_fmac_f32_e32 v79, v66, v66
	v_fmac_f32_e32 v80, v48, v48
	v_pk_fma_f32 v[68:69], v[14:15], v[68:69], v[94:95]
	v_add_f32_e32 v79, v79, v80
	v_add_f32_e32 v78, v79, v78
	v_mul_f32_e32 v79, v33, v33
	v_mul_f32_e32 v80, v69, v69
	v_fmac_f32_e32 v79, v32, v32
	v_fmac_f32_e32 v80, v68, v68
	v_add_f32_e32 v79, v79, v80
	v_add_f32_e32 v79, v79, v78
	s_nop 1
	v_div_fixup_f32 v78, v98, v97, 1.0
	v_pk_mul_f32 v[80:81], v[64:65], v[78:79] op_sel_hi:[1,0]
	v_pk_mul_f32 v[62:63], v[62:63], v[78:79] op_sel_hi:[1,0]
	s_waitcnt lgkmcnt(0)
	v_add_f32_dpp v79, v79, v79 quad_perm:[1,0,3,2] row_mask:0xf bank_mask:0xf
	s_nop 1
	v_pk_mul_f32 v[64:65], v[30:31], v[62:63]
	v_pk_mul_f32 v[62:63], v[28:29], v[80:81]
	v_pk_mul_f32 v[80:81], v[60:61], v[78:79] op_sel_hi:[1,0]
	v_pk_mul_f32 v[58:59], v[58:59], v[78:79] op_sel_hi:[1,0]
	s_waitcnt lgkmcnt(0)
	v_add_f32_dpp v79, v79, v79 quad_perm:[2,3,0,1] row_mask:0xf bank_mask:0xf
	s_nop 1
	v_pk_mul_f32 v[54:55], v[54:55], v[78:79] op_sel_hi:[1,0]
	v_pk_mul_f32 v[56:57], v[56:57], v[78:79] op_sel_hi:[1,0]
	v_pk_mul_f32 v[60:61], v[26:27], v[58:59]
	v_pk_mul_f32 v[58:59], v[24:25], v[80:81]
	s_waitcnt lgkmcnt(0)
	v_add_f32_dpp v79, v79, v79 row_half_mirror row_mask:0xf bank_mask:0xf
	s_nop 1
	v_pk_mul_f32 v[50:51], v[50:51], v[78:79] op_sel_hi:[1,0]
	v_pk_mul_f32 v[52:53], v[52:53], v[78:79] op_sel_hi:[1,0]
	v_pk_mul_f32 v[50:51], v[16:17], v[50:51]
	v_pk_mul_f32 v[52:53], v[18:19], v[52:53]
	s_waitcnt lgkmcnt(0)
	v_add_f32_dpp v80, v79, v79 row_mirror row_mask:0xf bank_mask:0xf
	ds_bpermute_b32 v81, v74, v80
	v_lshl_add_u64 v[78:79], v[44:45], 0, s[0:1]
	global_store_dwordx4 v[78:79], v[50:53], off
	v_pk_mul_f32 v[56:57], v[22:23], v[56:57]
	v_pk_mul_f32 v[54:55], v[20:21], v[54:55]
	s_waitcnt lgkmcnt(0)
	v_add_f32_e32 v50, v80, v81
	ds_bpermute_b32 v51, v75, v50
	global_store_dwordx4 v[78:79], v[54:57], off offset:1024
	global_store_dwordx4 v[78:79], v[58:61], off offset:2048
	global_store_dwordx4 v[78:79], v[62:65], off offset:3072
	s_cbranch_scc1 .LBB0_1552
	s_waitcnt lgkmcnt(0)
	v_add_f32_e32 v50, v50, v51
	v_fmamk_f32 v50, v50, 0x3a800000, v76
	v_mul_f32_e32 v51, 0x4f800000, v50
	v_cmp_gt_f32_e32 vcc, s8, v50
	s_ashr_i32 s7, s6, 31
	s_nop 0
	v_cndmask_b32_e32 v50, v50, v51, vcc
	v_sqrt_f32_e32 v51, v50
	s_nop 0
	v_add_u32_e32 v52, -1, v51
	v_fma_f32 v54, -v52, v51, v50
	v_add_u32_e32 v53, 1, v51
	v_cmp_ge_f32_e64 s[0:1], 0, v54
	s_nop 1
	v_cndmask_b32_e64 v52, v51, v52, s[0:1]
	v_fma_f32 v51, -v53, v51, v50
	v_cmp_lt_f32_e64 s[0:1], 0, v51
	s_nop 1
	v_cndmask_b32_e64 v51, v52, v53, s[0:1]
	v_mul_f32_e32 v52, 0x37800000, v51
	v_cndmask_b32_e32 v51, v51, v52, vcc
	v_cmp_class_f32_e32 vcc, v50, v77
	s_nop 1
	v_cndmask_b32_e32 v50, v51, v50, vcc
	v_div_scale_f32 v51, s[0:1], v50, v50, 1.0
	v_rcp_f32_e32 v52, v51
	s_lshl_b64 s[0:1], s[6:7], 12
	v_fma_f32 v53, -v51, v52, 1.0
	v_fmac_f32_e32 v52, v53, v52
	v_div_scale_f32 v53, vcc, 1.0, v50, 1.0
	v_mul_f32_e32 v54, v53, v52
	v_fma_f32 v55, -v51, v54, v53
	v_fmac_f32_e32 v54, v55, v52
	v_fma_f32 v51, -v51, v54, v53
	v_div_fmas_f32 v51, v51, v52, v54
	v_div_fixup_f32 v58, v51, v50, 1.0
	v_pk_mul_f32 v[32:33], v[32:33], v[58:59] op_sel_hi:[1,0]
	v_pk_mul_f32 v[50:51], v[68:69], v[58:59] op_sel_hi:[1,0]
	v_pk_mul_f32 v[34:35], v[34:35], v[58:59] op_sel_hi:[1,0]
	v_pk_mul_f32 v[52:53], v[30:31], v[50:51]
	v_pk_mul_f32 v[50:51], v[28:29], v[32:33]
	v_pk_mul_f32 v[32:33], v[66:67], v[58:59] op_sel_hi:[1,0]
	v_pk_mul_f32 v[48:49], v[48:49], v[58:59] op_sel_hi:[1,0]
	v_pk_mul_f32 v[54:55], v[24:25], v[32:33]
	v_pk_mul_f32 v[32:33], v[36:37], v[58:59] op_sel_hi:[1,0]
	v_pk_mul_f32 v[36:37], v[38:39], v[58:59] op_sel_hi:[1,0]
	v_pk_mul_f32 v[34:35], v[18:19], v[34:35]
	v_pk_mul_f32 v[38:39], v[22:23], v[36:37]
	v_pk_mul_f32 v[36:37], v[20:21], v[32:33]
	v_pk_mul_f32 v[32:33], v[46:47], v[58:59] op_sel_hi:[1,0]
	v_lshl_add_u64 v[46:47], v[44:45], 0, s[0:1]
	v_pk_mul_f32 v[32:33], v[16:17], v[32:33]
	v_pk_mul_f32 v[56:57], v[26:27], v[48:49]
	global_store_dwordx4 v[46:47], v[32:35], off
	global_store_dwordx4 v[46:47], v[36:39], off offset:1024
	global_store_dwordx4 v[46:47], v[54:57], off offset:2048
	global_store_dwordx4 v[46:47], v[50:53], off offset:3072
	s_branch .LBB0_1552
